# state and spatial units remapped for XCD-level L2 sharing of K/V tiles and LN-stat rows; spatial W fragments ks=0..5 prefetched at the loop top; state tile body regenerated
# speedup vs baseline: 1.0196x; 1.0051x over previous
; #define LAS __attribute__((address_space(3)))
; __device__ __forceinline__ void spatial_unit(LAS unsigned char* lds, const Args& a, int b, int n, int ghalf, int tid, int wid, int lane) {
;     bf16_t* Up = (bf16_t*)a.out; const bf16_t* VSp = (const bf16_t*)a.out + (size_t)MTOK * DM;
;     const bf16_t* Wb = (const bf16_t*)(a.ws + WS_SGW);
;     asm volatile("" : "+v"(lane)); asm volatile("" : "+v"(tid));
;     LAS f32x2* stats = (LAS f32x2*)(lds + LDS_STATS);
;     const int tok0 = b * SEQ + n * 128;
; #pragma unroll 1
;     for (int t0 = wid * 16; t0 < wid * 16 + 16; t0 += 4) {
; __global__ void __launch_bounds__(512, 2) fwd_megakernel(Args a) {
;     ...
;     for (int idx = bx; idx < 256; idx += G) { spatial_unit(lds, a, idx >> 5, (idx >> 1) & 15, idx & 1, tid, wid, lane); }
.LBB0_507:
	s_or_b64 exec, exec, s[0:1]
	s_cmpk_lt_i32 s2, 0x100
	s_cselect_b64 s[48:49], -1, 0
	s_cmpk_gt_i32 s2, 0xff
	s_waitcnt lgkmcnt(0)
	s_barrier
	s_cbranch_scc1 .LBB0_522
	s_and_b32 s98, s2, 0x7f
	s_lshl_b32 s98, s98, 1
	s_lshr_b32 s99, s2, 7
	s_or_b32 s98, s98, s99
	s_cmpk_eq_i32 s30, 0x100
	s_cselect_b32 s98, s98, s2
	s_lshl_b32 s0, s92, 5
	s_and_b32 s7, s0, 0x60
	s_lshl_b32 s0, s92, 7
	s_lshl_b32 s3, s92, 4
	s_add_i32 s10, s0, 0
	s_or_b32 s6, s3, 12
	s_and_b32 s8, s97, 0xffffff00
	s_add_i32 s9, s3, -4
	s_add_i32 s10, s10, 0x24400
	s_add_u32 s11, s26, 0x4003c00
	s_addc_u32 s14, s27, 0
	s_lshl_b32 s15, s98, 6
	s_lshl_b32 s22, s30, 6
	s_lshl_b32 s23, s98, 2
	s_lshl_b32 s33, s30, 2
	s_add_u32 s50, s26, s8
	s_addc_u32 s51, s27, 0
	s_or_b32 s34, s7, 24
	s_add_u32 s52, s28, 0x90080
	s_addc_u32 s53, s29, 0
	s_lshl_b32 s0, s97, 6
	s_and_b32 s44, s0, 0x3000
	s_add_u32 s40, s40, 16
	s_addc_u32 s41, s41, 0
	v_mbcnt_hi_u32_b32 v136, -1, v198
	s_add_u32 s42, s42, 16
	v_and_b32_e32 v0, 64, v136
	s_movk_i32 s35, 0x3000
	s_addc_u32 s43, s43, 0
	s_or_b32 s45, s7, 8
	s_or_b32 s54, s7, 16
	v_add_u32_e32 v137, 64, v0
	v_xor_b32_e32 v138, 1, v136
	v_xor_b32_e32 v139, 2, v136
	v_xor_b32_e32 v140, 4, v136
	v_xor_b32_e32 v141, 8, v136
	v_xor_b32_e32 v142, 16, v136
	v_xor_b32_e32 v143, 32, v136
	v_mov_b32_e32 v65, 0
	s_mov_b32 s56, 0x3a000000
	s_mov_b32 s55, 0xf800000
	v_mov_b32_e32 v144, 0x260
	s_movk_i32 s57, 0x1000
	s_movk_i32 s64, 0x2000
	s_mov_b64 s[58:59], 0x8000
	s_mov_b64 s[60:61], 0x400
	s_mov_b32 s65, s98
